# retc item epilogue: serial load-wait-store ladder over 16 column groups replaced by batched loads, counted waits, back-to-back stores
# speedup vs baseline: 1.0041x; 1.0041x over previous
.LBB0_359:
	s_or_b64 exec, exec, s[6:7]
	v_lshl_add_u32 v0, v145, 3, 0
	v_add_u32_e32 v0, 0x1a800, v0
	s_waitcnt lgkmcnt(0)
	s_barrier
	ds_read2st64_b64 v[66:69], v0 offset1:2
	v_readlane_b32 s6, v255, 26
	v_readlane_b32 s7, v255, 27
	s_lshl_b64 s[6:7], s[6:7], 2
	s_add_i32 s8, s8, s57
	v_lshl_add_u64 v[72:73], v[138:139], 0, s[6:7]
	s_waitcnt lgkmcnt(0)
	v_pk_add_f32 v[66:67], v[66:67], v[68:69]
	s_mov_b32 s6, 0x3b800000
	v_pk_mul_f32 v[66:67], v[66:67], s[6:7] op_sel_hi:[1,0]
	s_mov_b32 s6, 0x800000
	v_fma_f32 v0, -v66, v66, v67
	v_max_f32_e32 v0, 0, v0
	v_add_f32_e32 v0, 0x3727c5ac, v0
	v_cmp_gt_f32_e32 vcc, s6, v0
	v_mul_f32_e32 v68, 0x4b800000, v0
	v_lshl_or_b32 v70, v144, 2, s8
	v_cndmask_b32_e32 v0, v0, v68, vcc
	v_rsq_f32_e32 v0, v0
	s_mov_b64 s[6:7], 0x5000
	v_ashrrev_i32_e32 v71, 31, v70
	v_lshlrev_b64 v[80:81], 1, v[70:71]
	v_mul_f32_e32 v68, 0x45800000, v0
	v_cndmask_b32_e32 v0, v0, v68, vcc
	v_lshl_add_u64 v[68:69], v[142:143], 0, s[6:7]
	v_lshlrev_b64 v[74:75], 13, v[140:141]
	v_lshl_add_u64 v[72:73], v[70:71], 2, v[72:73]
	v_lshl_add_u64 v[82:83], v[68:69], 0, v[80:81]
	v_lshl_add_u64 v[78:79], s[0:1], 0, v[74:75]
	global_load_dwordx4 v[74:77], v[72:73], off
	v_pk_add_f32 v[50:51], v[50:51], v[66:67] op_sel_hi:[1,0] neg_lo:[0,1] neg_hi:[0,1]
	global_load_dwordx2 v[82:83], v[82:83], off
	v_pk_mul_f32 v[50:51], v[50:51], v[0:1] op_sel_hi:[1,0]
	v_pk_add_f32 v[52:53], v[52:53], v[66:67] op_sel_hi:[1,0] neg_lo:[0,1] neg_hi:[0,1]
	s_mov_b64 s[0:1], 0x2aac1200
	v_pk_mul_f32 v[52:53], v[52:53], v[0:1] op_sel_hi:[1,0]
	v_pk_add_f32 v[54:55], v[54:55], v[66:67] op_sel_hi:[1,0] neg_lo:[0,1] neg_hi:[0,1]
	v_pk_add_f32 v[56:57], v[56:57], v[66:67] op_sel_hi:[1,0] neg_lo:[0,1] neg_hi:[0,1]
	v_pk_mul_f32 v[54:55], v[54:55], v[0:1] op_sel_hi:[1,0]
	v_pk_mul_f32 v[56:57], v[56:57], v[0:1] op_sel_hi:[1,0]
	v_pk_add_f32 v[58:59], v[58:59], v[66:67] op_sel_hi:[1,0] neg_lo:[0,1] neg_hi:[0,1]
	v_pk_add_f32 v[34:35], v[34:35], v[66:67] op_sel_hi:[1,0] neg_lo:[0,1] neg_hi:[0,1]
	v_pk_mul_f32 v[58:59], v[58:59], v[0:1] op_sel_hi:[1,0]
	v_pk_mul_f32 v[34:35], v[34:35], v[0:1] op_sel_hi:[1,0]
	v_pk_add_f32 v[36:37], v[36:37], v[66:67] op_sel_hi:[1,0] neg_lo:[0,1] neg_hi:[0,1]
	v_pk_add_f32 v[38:39], v[38:39], v[66:67] op_sel_hi:[1,0] neg_lo:[0,1] neg_hi:[0,1]
	v_pk_mul_f32 v[36:37], v[36:37], v[0:1] op_sel_hi:[1,0]
	v_pk_mul_f32 v[38:39], v[38:39], v[0:1] op_sel_hi:[1,0]
	v_pk_add_f32 v[18:19], v[18:19], v[66:67] op_sel_hi:[1,0] neg_lo:[0,1] neg_hi:[0,1]
	v_pk_add_f32 v[20:21], v[20:21], v[66:67] op_sel_hi:[1,0] neg_lo:[0,1] neg_hi:[0,1]
	v_pk_mul_f32 v[18:19], v[18:19], v[0:1] op_sel_hi:[1,0]
	v_pk_mul_f32 v[20:21], v[20:21], v[0:1] op_sel_hi:[1,0]
	v_pk_add_f32 v[22:23], v[22:23], v[66:67] op_sel_hi:[1,0] neg_lo:[0,1] neg_hi:[0,1]
	v_pk_add_f32 v[2:3], v[2:3], v[66:67] op_sel_hi:[1,0] neg_lo:[0,1] neg_hi:[0,1]
	v_pk_mul_f32 v[22:23], v[22:23], v[0:1] op_sel_hi:[1,0]
	v_pk_mul_f32 v[2:3], v[2:3], v[0:1] op_sel_hi:[1,0]
	v_pk_add_f32 v[4:5], v[4:5], v[66:67] op_sel_hi:[1,0] neg_lo:[0,1] neg_hi:[0,1]
	v_pk_add_f32 v[6:7], v[6:7], v[66:67] op_sel_hi:[1,0] neg_lo:[0,1] neg_hi:[0,1]
	v_pk_mul_f32 v[4:5], v[4:5], v[0:1] op_sel_hi:[1,0]
	v_pk_mul_f32 v[6:7], v[6:7], v[0:1] op_sel_hi:[1,0]
	s_waitcnt vmcnt(1)
	v_pk_mul_f32 v[50:51], v[74:75], v[50:51]
	v_pk_mul_f32 v[52:53], v[76:77], v[52:53]
	s_waitcnt vmcnt(0)
	v_lshlrev_b32_e32 v74, 16, v82
	v_and_b32_e32 v75, 0xffff0000, v82
	v_pk_mul_f32 v[50:51], v[50:51], v[74:75]
	v_lshlrev_b32_e32 v74, 16, v83
	v_and_b32_e32 v75, 0xffff0000, v83
	v_pk_mul_f32 v[52:53], v[52:53], v[74:75]
	v_cvt_pk_bf16_f32 v74, v50, v51
	v_cvt_pk_bf16_f32 v75, v52, v53
	v_lshl_add_u64 v[52:53], v[78:79], 0, v[80:81]
	v_lshl_add_u64 v[50:51], v[52:53], 0, s[0:1]
	s_mov_b32 s0, 0x2aac1000
	v_add_co_u32_e32 v52, vcc, s0, v52
	s_mov_b64 s[0:1], 0
	s_nop 0
	v_addc_co_u32_e32 v53, vcc, 0, v53, vcc
	global_store_dwordx2 v[52:53], v[74:75], off offset:512
	v_lshl_add_u64 v[152:153], v[68:69], 0, v[80:81]
	global_load_dwordx4 v[84:87], v[72:73], off offset:32
	global_load_dwordx2 v[178:179], v[152:153], off offset:16
	global_load_dwordx4 v[88:91], v[72:73], off offset:64
	global_load_dwordx2 v[180:181], v[152:153], off offset:32
	global_load_dwordx4 v[92:95], v[72:73], off offset:96
	global_load_dwordx2 v[182:183], v[152:153], off offset:48
	global_load_dwordx4 v[96:99], v[72:73], off offset:128
	global_load_dwordx2 v[184:185], v[152:153], off offset:64
	global_load_dwordx4 v[100:103], v[72:73], off offset:160
	global_load_dwordx2 v[186:187], v[152:153], off offset:80
	global_load_dwordx4 v[104:107], v[72:73], off offset:192
	global_load_dwordx2 v[188:189], v[152:153], off offset:96
	global_load_dwordx4 v[108:111], v[72:73], off offset:224
	global_load_dwordx2 v[190:191], v[152:153], off offset:112
	global_load_dwordx4 v[112:115], v[72:73], off offset:256
	global_load_dwordx2 v[192:193], v[152:153], off offset:128
	global_load_dwordx4 v[116:119], v[72:73], off offset:288
	global_load_dwordx2 v[194:195], v[152:153], off offset:144
	global_load_dwordx4 v[120:123], v[72:73], off offset:320
	global_load_dwordx2 v[196:197], v[152:153], off offset:160
	global_load_dwordx4 v[124:127], v[72:73], off offset:352
	global_load_dwordx2 v[198:199], v[152:153], off offset:176
	global_load_dwordx4 v[128:131], v[72:73], off offset:384
	global_load_dwordx2 v[200:201], v[152:153], off offset:192
	global_load_dwordx4 v[132:135], v[72:73], off offset:416
	global_load_dwordx2 v[202:203], v[152:153], off offset:208
	global_load_dwordx4 v[160:163], v[72:73], off offset:448
	global_load_dwordx2 v[204:205], v[152:153], off offset:224
	global_load_dwordx4 v[164:167], v[72:73], off offset:480
	global_load_dwordx2 v[206:207], v[152:153], off offset:240
	v_pk_add_f32 v[60:61], v[60:61], v[66:67] op_sel_hi:[1,0] neg_lo:[0,1] neg_hi:[0,1]
	v_pk_mul_f32 v[60:61], v[60:61], v[0:1] op_sel_hi:[1,0]
	v_pk_add_f32 v[62:63], v[62:63], v[66:67] op_sel_hi:[1,0] neg_lo:[0,1] neg_hi:[0,1]
	v_pk_mul_f32 v[62:63], v[62:63], v[0:1] op_sel_hi:[1,0]
	v_pk_add_f32 v[64:65], v[64:65], v[66:67] op_sel_hi:[1,0] neg_lo:[0,1] neg_hi:[0,1]
	v_pk_mul_f32 v[64:65], v[64:65], v[0:1] op_sel_hi:[1,0]
	v_pk_add_f32 v[40:41], v[40:41], v[66:67] op_sel_hi:[1,0] neg_lo:[0,1] neg_hi:[0,1]
	v_pk_mul_f32 v[40:41], v[40:41], v[0:1] op_sel_hi:[1,0]
	v_pk_add_f32 v[42:43], v[42:43], v[66:67] op_sel_hi:[1,0] neg_lo:[0,1] neg_hi:[0,1]
	v_pk_mul_f32 v[42:43], v[42:43], v[0:1] op_sel_hi:[1,0]
	v_pk_add_f32 v[44:45], v[44:45], v[66:67] op_sel_hi:[1,0] neg_lo:[0,1] neg_hi:[0,1]
	v_pk_mul_f32 v[44:45], v[44:45], v[0:1] op_sel_hi:[1,0]
	v_pk_add_f32 v[46:47], v[46:47], v[66:67] op_sel_hi:[1,0] neg_lo:[0,1] neg_hi:[0,1]
	v_pk_mul_f32 v[46:47], v[46:47], v[0:1] op_sel_hi:[1,0]
	v_pk_add_f32 v[48:49], v[48:49], v[66:67] op_sel_hi:[1,0] neg_lo:[0,1] neg_hi:[0,1]
	v_pk_mul_f32 v[48:49], v[48:49], v[0:1] op_sel_hi:[1,0]
	v_pk_add_f32 v[24:25], v[24:25], v[66:67] op_sel_hi:[1,0] neg_lo:[0,1] neg_hi:[0,1]
	v_pk_mul_f32 v[24:25], v[24:25], v[0:1] op_sel_hi:[1,0]
	v_pk_add_f32 v[26:27], v[26:27], v[66:67] op_sel_hi:[1,0] neg_lo:[0,1] neg_hi:[0,1]
	v_pk_mul_f32 v[26:27], v[26:27], v[0:1] op_sel_hi:[1,0]
	v_pk_add_f32 v[28:29], v[28:29], v[66:67] op_sel_hi:[1,0] neg_lo:[0,1] neg_hi:[0,1]
	v_pk_mul_f32 v[28:29], v[28:29], v[0:1] op_sel_hi:[1,0]
	v_pk_add_f32 v[30:31], v[30:31], v[66:67] op_sel_hi:[1,0] neg_lo:[0,1] neg_hi:[0,1]
	v_pk_mul_f32 v[30:31], v[30:31], v[0:1] op_sel_hi:[1,0]
	v_pk_add_f32 v[32:33], v[32:33], v[66:67] op_sel_hi:[1,0] neg_lo:[0,1] neg_hi:[0,1]
	v_pk_mul_f32 v[32:33], v[32:33], v[0:1] op_sel_hi:[1,0]
	v_pk_add_f32 v[8:9], v[8:9], v[66:67] op_sel_hi:[1,0] neg_lo:[0,1] neg_hi:[0,1]
	v_pk_mul_f32 v[8:9], v[8:9], v[0:1] op_sel_hi:[1,0]
	v_pk_add_f32 v[10:11], v[10:11], v[66:67] op_sel_hi:[1,0] neg_lo:[0,1] neg_hi:[0,1]
	v_pk_mul_f32 v[10:11], v[10:11], v[0:1] op_sel_hi:[1,0]
	v_pk_add_f32 v[12:13], v[12:13], v[66:67] op_sel_hi:[1,0] neg_lo:[0,1] neg_hi:[0,1]
	v_pk_mul_f32 v[12:13], v[12:13], v[0:1] op_sel_hi:[1,0]
	v_pk_add_f32 v[14:15], v[14:15], v[66:67] op_sel_hi:[1,0] neg_lo:[0,1] neg_hi:[0,1]
	v_pk_mul_f32 v[14:15], v[14:15], v[0:1] op_sel_hi:[1,0]
	v_pk_add_f32 v[16:17], v[16:17], v[66:67] op_sel_hi:[1,0] neg_lo:[0,1] neg_hi:[0,1]
	v_pk_mul_f32 v[16:17], v[16:17], v[0:1] op_sel_hi:[1,0]
	s_waitcnt vmcnt(28)
	v_pk_mul_f32 v[54:55], v[54:55], v[84:85]
	v_pk_mul_f32 v[56:57], v[56:57], v[86:87]
	v_lshlrev_b32_e32 v74, 16, v178
	v_and_b32_e32 v75, 0xffff0000, v178
	v_lshlrev_b32_e32 v76, 16, v179
	v_and_b32_e32 v77, 0xffff0000, v179
	v_pk_mul_f32 v[54:55], v[54:55], v[74:75]
	v_pk_mul_f32 v[56:57], v[56:57], v[76:77]
	v_cvt_pk_bf16_f32 v154, v54, v55
	v_cvt_pk_bf16_f32 v155, v56, v57
	global_store_dwordx2 v[50:51], v[154:155], off offset:16
	s_waitcnt vmcnt(27)
	v_pk_mul_f32 v[58:59], v[58:59], v[88:89]
	v_pk_mul_f32 v[60:61], v[60:61], v[90:91]
	v_lshlrev_b32_e32 v74, 16, v180
	v_and_b32_e32 v75, 0xffff0000, v180
	v_lshlrev_b32_e32 v76, 16, v181
	v_and_b32_e32 v77, 0xffff0000, v181
	v_pk_mul_f32 v[58:59], v[58:59], v[74:75]
	v_pk_mul_f32 v[60:61], v[60:61], v[76:77]
	v_cvt_pk_bf16_f32 v154, v58, v59
	v_cvt_pk_bf16_f32 v155, v60, v61
	global_store_dwordx2 v[50:51], v[154:155], off offset:32
	s_waitcnt vmcnt(26)
	v_pk_mul_f32 v[62:63], v[62:63], v[92:93]
	v_pk_mul_f32 v[64:65], v[64:65], v[94:95]
	v_lshlrev_b32_e32 v74, 16, v182
	v_and_b32_e32 v75, 0xffff0000, v182
	v_lshlrev_b32_e32 v76, 16, v183
	v_and_b32_e32 v77, 0xffff0000, v183
	v_pk_mul_f32 v[62:63], v[62:63], v[74:75]
	v_pk_mul_f32 v[64:65], v[64:65], v[76:77]
	v_cvt_pk_bf16_f32 v154, v62, v63
	v_cvt_pk_bf16_f32 v155, v64, v65
	global_store_dwordx2 v[50:51], v[154:155], off offset:48
	s_waitcnt vmcnt(25)
	v_pk_mul_f32 v[34:35], v[34:35], v[96:97]
	v_pk_mul_f32 v[36:37], v[36:37], v[98:99]
	v_lshlrev_b32_e32 v74, 16, v184
	v_and_b32_e32 v75, 0xffff0000, v184
	v_lshlrev_b32_e32 v76, 16, v185
	v_and_b32_e32 v77, 0xffff0000, v185
	v_pk_mul_f32 v[34:35], v[34:35], v[74:75]
	v_pk_mul_f32 v[36:37], v[36:37], v[76:77]
	v_cvt_pk_bf16_f32 v154, v34, v35
	v_cvt_pk_bf16_f32 v155, v36, v37
	global_store_dwordx2 v[50:51], v[154:155], off offset:64
	s_waitcnt vmcnt(24)
	v_pk_mul_f32 v[38:39], v[38:39], v[100:101]
	v_pk_mul_f32 v[40:41], v[40:41], v[102:103]
	v_lshlrev_b32_e32 v74, 16, v186
	v_and_b32_e32 v75, 0xffff0000, v186
	v_lshlrev_b32_e32 v76, 16, v187
	v_and_b32_e32 v77, 0xffff0000, v187
	v_pk_mul_f32 v[38:39], v[38:39], v[74:75]
	v_pk_mul_f32 v[40:41], v[40:41], v[76:77]
	v_cvt_pk_bf16_f32 v154, v38, v39
	v_cvt_pk_bf16_f32 v155, v40, v41
	global_store_dwordx2 v[50:51], v[154:155], off offset:80
	s_waitcnt vmcnt(23)
	v_pk_mul_f32 v[42:43], v[42:43], v[104:105]
	v_pk_mul_f32 v[44:45], v[44:45], v[106:107]
	v_lshlrev_b32_e32 v74, 16, v188
	v_and_b32_e32 v75, 0xffff0000, v188
	v_lshlrev_b32_e32 v76, 16, v189
	v_and_b32_e32 v77, 0xffff0000, v189
	v_pk_mul_f32 v[42:43], v[42:43], v[74:75]
	v_pk_mul_f32 v[44:45], v[44:45], v[76:77]
	v_cvt_pk_bf16_f32 v154, v42, v43
	v_cvt_pk_bf16_f32 v155, v44, v45
	global_store_dwordx2 v[50:51], v[154:155], off offset:96
	s_waitcnt vmcnt(22)
	v_pk_mul_f32 v[46:47], v[46:47], v[108:109]
	v_pk_mul_f32 v[48:49], v[48:49], v[110:111]
	v_lshlrev_b32_e32 v74, 16, v190
	v_and_b32_e32 v75, 0xffff0000, v190
	v_lshlrev_b32_e32 v76, 16, v191
	v_and_b32_e32 v77, 0xffff0000, v191
	v_pk_mul_f32 v[46:47], v[46:47], v[74:75]
	v_pk_mul_f32 v[48:49], v[48:49], v[76:77]
	v_cvt_pk_bf16_f32 v154, v46, v47
	v_cvt_pk_bf16_f32 v155, v48, v49
	global_store_dwordx2 v[50:51], v[154:155], off offset:112
	s_waitcnt vmcnt(21)
	v_pk_mul_f32 v[18:19], v[18:19], v[112:113]
	v_pk_mul_f32 v[20:21], v[20:21], v[114:115]
	v_lshlrev_b32_e32 v74, 16, v192
	v_and_b32_e32 v75, 0xffff0000, v192
	v_lshlrev_b32_e32 v76, 16, v193
	v_and_b32_e32 v77, 0xffff0000, v193
	v_pk_mul_f32 v[18:19], v[18:19], v[74:75]
	v_pk_mul_f32 v[20:21], v[20:21], v[76:77]
	v_cvt_pk_bf16_f32 v154, v18, v19
	v_cvt_pk_bf16_f32 v155, v20, v21
	global_store_dwordx2 v[50:51], v[154:155], off offset:128
	s_waitcnt vmcnt(20)
	v_pk_mul_f32 v[22:23], v[22:23], v[116:117]
	v_pk_mul_f32 v[24:25], v[24:25], v[118:119]
	v_lshlrev_b32_e32 v74, 16, v194
	v_and_b32_e32 v75, 0xffff0000, v194
	v_lshlrev_b32_e32 v76, 16, v195
	v_and_b32_e32 v77, 0xffff0000, v195
	v_pk_mul_f32 v[22:23], v[22:23], v[74:75]
	v_pk_mul_f32 v[24:25], v[24:25], v[76:77]
	v_cvt_pk_bf16_f32 v154, v22, v23
	v_cvt_pk_bf16_f32 v155, v24, v25
	global_store_dwordx2 v[50:51], v[154:155], off offset:144
	s_waitcnt vmcnt(19)
	v_pk_mul_f32 v[26:27], v[26:27], v[120:121]
	v_pk_mul_f32 v[28:29], v[28:29], v[122:123]
	v_lshlrev_b32_e32 v74, 16, v196
	v_and_b32_e32 v75, 0xffff0000, v196
	v_lshlrev_b32_e32 v76, 16, v197
	v_and_b32_e32 v77, 0xffff0000, v197
	v_pk_mul_f32 v[26:27], v[26:27], v[74:75]
	v_pk_mul_f32 v[28:29], v[28:29], v[76:77]
	v_cvt_pk_bf16_f32 v154, v26, v27
	v_cvt_pk_bf16_f32 v155, v28, v29
	global_store_dwordx2 v[50:51], v[154:155], off offset:160
	s_waitcnt vmcnt(18)
	v_pk_mul_f32 v[30:31], v[30:31], v[124:125]
	v_pk_mul_f32 v[32:33], v[32:33], v[126:127]
	v_lshlrev_b32_e32 v74, 16, v198
	v_and_b32_e32 v75, 0xffff0000, v198
	v_lshlrev_b32_e32 v76, 16, v199
	v_and_b32_e32 v77, 0xffff0000, v199
	v_pk_mul_f32 v[30:31], v[30:31], v[74:75]
	v_pk_mul_f32 v[32:33], v[32:33], v[76:77]
	v_cvt_pk_bf16_f32 v154, v30, v31
	v_cvt_pk_bf16_f32 v155, v32, v33
	global_store_dwordx2 v[50:51], v[154:155], off offset:176
	s_waitcnt vmcnt(17)
	v_pk_mul_f32 v[2:3], v[2:3], v[128:129]
	v_pk_mul_f32 v[4:5], v[4:5], v[130:131]
	v_lshlrev_b32_e32 v74, 16, v200
	v_and_b32_e32 v75, 0xffff0000, v200
	v_lshlrev_b32_e32 v76, 16, v201
	v_and_b32_e32 v77, 0xffff0000, v201
	v_pk_mul_f32 v[2:3], v[2:3], v[74:75]
	v_pk_mul_f32 v[4:5], v[4:5], v[76:77]
	v_cvt_pk_bf16_f32 v154, v2, v3
	v_cvt_pk_bf16_f32 v155, v4, v5
	global_store_dwordx2 v[50:51], v[154:155], off offset:192
	s_waitcnt vmcnt(16)
	v_pk_mul_f32 v[6:7], v[6:7], v[132:133]
	v_pk_mul_f32 v[8:9], v[8:9], v[134:135]
	v_lshlrev_b32_e32 v74, 16, v202
	v_and_b32_e32 v75, 0xffff0000, v202
	v_lshlrev_b32_e32 v76, 16, v203
	v_and_b32_e32 v77, 0xffff0000, v203
	v_pk_mul_f32 v[6:7], v[6:7], v[74:75]
	v_pk_mul_f32 v[8:9], v[8:9], v[76:77]
	v_cvt_pk_bf16_f32 v154, v6, v7
	v_cvt_pk_bf16_f32 v155, v8, v9
	global_store_dwordx2 v[50:51], v[154:155], off offset:208
	s_waitcnt vmcnt(15)
	v_pk_mul_f32 v[10:11], v[10:11], v[160:161]
	v_pk_mul_f32 v[12:13], v[12:13], v[162:163]
	v_lshlrev_b32_e32 v74, 16, v204
	v_and_b32_e32 v75, 0xffff0000, v204
	v_lshlrev_b32_e32 v76, 16, v205
	v_and_b32_e32 v77, 0xffff0000, v205
	v_pk_mul_f32 v[10:11], v[10:11], v[74:75]
	v_pk_mul_f32 v[12:13], v[12:13], v[76:77]
	v_cvt_pk_bf16_f32 v154, v10, v11
	v_cvt_pk_bf16_f32 v155, v12, v13
	global_store_dwordx2 v[50:51], v[154:155], off offset:224
	s_waitcnt vmcnt(14)
	v_pk_mul_f32 v[14:15], v[14:15], v[164:165]
	v_pk_mul_f32 v[16:17], v[16:17], v[166:167]
	v_lshlrev_b32_e32 v74, 16, v206
	v_and_b32_e32 v75, 0xffff0000, v206
	v_lshlrev_b32_e32 v76, 16, v207
	v_and_b32_e32 v77, 0xffff0000, v207
	v_pk_mul_f32 v[14:15], v[14:15], v[74:75]
	v_pk_mul_f32 v[16:17], v[16:17], v[76:77]
	v_cvt_pk_bf16_f32 v154, v14, v15
	v_cvt_pk_bf16_f32 v155, v16, v17
	global_store_dwordx2 v[50:51], v[154:155], off offset:240
	s_barrier
